# k-loop DMA block spread over the first 6 of the 8 last-group MFMA slots (completes the placement curve: 4 slots 1.044, 8 slots best)
# baseline (speedup 1.0000x reference)
; #define MFMA(a, b, c) __builtin_amdgcn_mfma_f32_32x32x16_bf16((a), (b), (c), 0, 0, 0)
;     ...
;     auto issue_at = [&](int mm0, int nn0, int kt, int buf) {
;       char* lb = L0 + buf * BUFB;
; #pragma unroll
;       for (int i = 0; i < 4; ++i) {
;         const int seg = wv * 4 + i, row = seg * 8 + gl_row;
;         const int c = (lane & 7) ^ ((row >> 1) & 7);
;         const u16* ap = (kt < g.split) ? g.a0 + (size_t)(mm0 + row) * g.ld0 + kt * g.ks0 : g.a1 + (size_t)(mm0 + row) * g.ld1 + (kt - g.split) * 64;
;         __builtin_amdgcn_global_load_lds((const unsigned*)(ap + c * 8), (__attribute__((address_space(3))) unsigned*)(lb + seg * 1024 + lane * 16), 16, 0, 0);
;       }
; #pragma unroll
;       for (int i = 0; i < BN / 64; ++i) {
;         const int seg = wv * (BN / 64) + i, row = seg * 8 + gl_row;
;         const int c = (lane & 7) ^ ((row >> 1) & 7);
;         __builtin_amdgcn_global_load_lds((const unsigned*)(g.W + (size_t)(nn0 + row) * g.K + kt * 64 + c * 8),
;                                          (__attribute__((address_space(3))) unsigned*)(lb + 256 * 128 + seg * 1024 + lane * 16), 16, 0, 0);
;       }
;     };
;     auto issue = [&](int kt, int buf) { issue_at(m0, n0, kt, buf); };
;     auto compute2 = [&](int buf) {
;       const char* lb = L0 + buf * BUFB;
; #pragma unroll
;       for (int ks = 0; ks < 4; ++ks) {
;         const int c = ks * 2 + hh;
;         bf16x8 wf[2], xf[MI];
; #pragma unroll
;         for (int j = 0; j < 2; ++j) { const int r = wn * 64 + j * 32 + l32; wf[j] = *(const bf16x8*)(lb + 256 * 128 + r * 128 + ((c ^ ((r >> 1) & 7)) << 4)); }
; #pragma unroll
;         for (int i = 0; i < MI; ++i) { const int r = wm * (MI * 32) + i * 32 + l32; xf[i] = *(const bf16x8*)(lb + r * 128 + ((c ^ ((r >> 1) & 7)) << 4)); }
; #pragma unroll
;         for (int i = 0; i < MI; ++i) {
;           acc[i][0] = MFMA(wf[0], xf[i], acc[i][0]);
;           acc[i][1] = MFMA(wf[1], xf[i], acc[i][1]);
;         }
;       }
;     };
;     ...
;       for (int kt = 0; kt < nk; ++kt) {
;         const int buf = kt & 1;
;         if (kt + 1 < nk) issue(kt + 1, buf ^ 1);
;         else if (chain & 2) issue_at(nmt * 256, nnt * BN, 0, buf ^ 1);
;         compute2(buf);
;         asm volatile("s_waitcnt vmcnt(0)" ::: "memory");
;         __syncthreads();
;       }
.Lgemm_g1_798:
	v_add_u32_e32 v0, s14, v173
	v_add_u32_e32 v176, v0, v171
	v_add_u32_e32 v0, v0, v170
	s_waitcnt lgkmcnt(3)
	v_mfma_f32_32x32x16_bf16 v[114:129], v[224:227], v[232:235], v[114:129]
	ds_read_b128 v[200:203], v176 offset:32768
	v_mfma_f32_32x32x16_bf16 v[98:113], v[228:231], v[232:235], v[98:113]
	ds_read_b128 v[204:207], v176 offset:36864
	s_waitcnt lgkmcnt(4)
	v_mfma_f32_32x32x16_bf16 v[82:97], v[224:227], v[240:243], v[82:97]
	ds_read_b128 v[208:211], v0
	v_mfma_f32_32x32x16_bf16 v[66:81], v[228:231], v[240:243], v[66:81]
	ds_read_b128 v[212:215], v0 offset:4096
	s_waitcnt lgkmcnt(5)
	v_mfma_f32_32x32x16_bf16 v[50:65], v[224:227], v[244:247], v[50:65]
	ds_read_b128 v[216:219], v0 offset:8192
	v_mfma_f32_32x32x16_bf16 v[34:49], v[228:231], v[244:247], v[34:49]
	ds_read_b128 v[220:223], v0 offset:12288
	s_waitcnt lgkmcnt(6)
	v_mfma_f32_32x32x16_bf16 v[18:33], v[224:227], v[248:251], v[18:33]
	v_mfma_f32_32x32x16_bf16 v[2:17], v[228:231], v[248:251], v[2:17]
	v_add_u32_e32 v0, s14, v172
	v_add_u32_e32 v176, v0, v171
	v_add_u32_e32 v0, v0, v170
	s_waitcnt lgkmcnt(3)
	v_mfma_f32_32x32x16_bf16 v[114:129], v[200:203], v[208:211], v[114:129]
	ds_read_b128 v[224:227], v176 offset:32768
	v_mfma_f32_32x32x16_bf16 v[98:113], v[204:207], v[208:211], v[98:113]
	ds_read_b128 v[228:231], v176 offset:36864
	s_waitcnt lgkmcnt(4)
	v_mfma_f32_32x32x16_bf16 v[82:97], v[200:203], v[212:215], v[82:97]
	ds_read_b128 v[232:235], v0
	v_mfma_f32_32x32x16_bf16 v[66:81], v[204:207], v[212:215], v[66:81]
	ds_read_b128 v[240:243], v0 offset:4096
	s_waitcnt lgkmcnt(5)
	v_mfma_f32_32x32x16_bf16 v[50:65], v[200:203], v[216:219], v[50:65]
	ds_read_b128 v[244:247], v0 offset:8192
	v_mfma_f32_32x32x16_bf16 v[34:49], v[204:207], v[216:219], v[34:49]
	ds_read_b128 v[248:251], v0 offset:12288
	s_waitcnt lgkmcnt(6)
	v_mfma_f32_32x32x16_bf16 v[18:33], v[200:203], v[220:223], v[18:33]
	v_mfma_f32_32x32x16_bf16 v[2:17], v[204:207], v[220:223], v[2:17]
	s_waitcnt vmcnt(0)
	s_waitcnt vmcnt(0) lgkmcnt(0)
	s_barrier
	s_cbranch_scc1 .Lgemm_exit_798
	s_and_b32 s14, s11, 0x10000
	s_xor_b32 s15, s14, 0x10000
	s_add_i32 s15, s15, 0
	s_add_i32 s14, s14, 0
	v_add_u32_e32 v0, s14, v175
	v_add_u32_e32 v176, v0, v171
	v_add_u32_e32 v0, v0, v170
	ds_read_b128 v[200:203], v176 offset:32768
	ds_read_b128 v[204:207], v176 offset:36864
	ds_read_b128 v[208:211], v0
	ds_read_b128 v[212:215], v0 offset:4096
	ds_read_b128 v[216:219], v0 offset:8192
	ds_read_b128 v[220:223], v0 offset:12288
	v_mfma_f32_32x32x16_bf16 v[114:129], v[224:227], v[232:235], v[114:129]
	s_add_i32 s64, s15, 0x8000
	s_add_i32 m0, s15, s60
	v_lshl_add_u64 v[176:177], v[152:153], 0, s[2:3]
	global_load_lds_dwordx4 v[176:177], off
	s_add_i32 m0, s15, s61
	v_mfma_f32_32x32x16_bf16 v[98:113], v[228:231], v[232:235], v[98:113]
	v_lshl_add_u64 v[176:177], v[150:151], 0, s[2:3]
	global_load_lds_dwordx4 v[176:177], off
	s_add_i32 m0, s15, s62
	v_lshl_add_u64 v[176:177], v[148:149], 0, s[2:3]
	global_load_lds_dwordx4 v[176:177], off
	v_mfma_f32_32x32x16_bf16 v[82:97], v[224:227], v[240:243], v[82:97]
	s_add_i32 m0, s15, s63
	v_lshl_add_u64 v[176:177], v[146:147], 0, s[2:3]
	global_load_lds_dwordx4 v[176:177], off
	s_add_i32 m0, s64, s60
	v_lshl_add_u64 v[176:177], v[144:145], 0, s[2:3]
	v_mfma_f32_32x32x16_bf16 v[66:81], v[228:231], v[240:243], v[66:81]
	global_load_lds_dwordx4 v[176:177], off
	s_add_i32 m0, s64, s61
	v_lshl_add_u64 v[176:177], v[142:143], 0, s[2:3]
	global_load_lds_dwordx4 v[176:177], off
	s_add_i32 m0, s64, s62
	v_mfma_f32_32x32x16_bf16 v[50:65], v[224:227], v[244:247], v[50:65]
	v_lshl_add_u64 v[176:177], v[140:141], 0, s[2:3]
	global_load_lds_dwordx4 v[176:177], off
	s_add_i32 m0, s64, s63
	v_lshl_add_u64 v[176:177], v[138:139], 0, s[2:3]
	global_load_lds_dwordx4 v[176:177], off
	v_mfma_f32_32x32x16_bf16 v[34:49], v[228:231], v[244:247], v[34:49]
	v_mfma_f32_32x32x16_bf16 v[18:33], v[224:227], v[248:251], v[18:33]
	v_mfma_f32_32x32x16_bf16 v[2:17], v[228:231], v[248:251], v[2:17]
	s_branch .Lgemm_rot_798

; #define MFMA(a, b, c) __builtin_amdgcn_mfma_f32_32x32x16_bf16((a), (b), (c), 0, 0, 0)
;     ...
;     auto compute2 = [&](int buf) {
;       const char* lb = L0 + buf * BUFB;
; #pragma unroll
;       for (int ks = 0; ks < 4; ++ks) {
;         const int c = ks * 2 + hh;
;         bf16x8 wf[2], xf[MI];
; #pragma unroll
;         for (int j = 0; j < 2; ++j) { const int r = wn * 64 + j * 32 + l32; wf[j] = *(const bf16x8*)(lb + 256 * 128 + r * 128 + ((c ^ ((r >> 1) & 7)) << 4)); }
; #pragma unroll
;         for (int i = 0; i < MI; ++i) { const int r = wm * (MI * 32) + i * 32 + l32; xf[i] = *(const bf16x8*)(lb + r * 128 + ((c ^ ((r >> 1) & 7)) << 4)); }
; #pragma unroll
;         for (int i = 0; i < MI; ++i) {
;           acc[i][0] = MFMA(wf[0], xf[i], acc[i][0]);
;           acc[i][1] = MFMA(wf[1], xf[i], acc[i][1]);
;         }
;       }
;     };
;     if (NBUF == 3) {
;       issue(0, 0);
;       if (nk > 1) { issue(1, 1); if (BN == 128) asm volatile("s_waitcnt vmcnt(6)" ::: "memory"); else asm volatile("s_waitcnt vmcnt(5)" ::: "memory"); }
;       else asm volatile("s_waitcnt vmcnt(0)" ::: "memory");
;       asm volatile("s_waitcnt lgkmcnt(0)" ::: "memory");
;       __builtin_amdgcn_s_barrier();
;       int buf = 0;
;       for (int kt = 0; kt < nk; ++kt) {
;         const int b2 = buf == 0 ? 2 : buf - 1;
;         if (kt + 2 < nk) issue(kt + 2, b2);
;         compute2(buf);
;         if (kt + 2 < nk) { if (BN == 128) asm volatile("s_waitcnt vmcnt(6)" ::: "memory"); else asm volatile("s_waitcnt vmcnt(5)" ::: "memory"); }
;         else asm volatile("s_waitcnt vmcnt(0)" ::: "memory");
;         asm volatile("s_waitcnt lgkmcnt(0)" ::: "memory");
;         __builtin_amdgcn_s_barrier();
;         buf = buf == 2 ? 0 : buf + 1;
;       }
;     } else {
;       if (!(chain & 1)) {
;         issue(0, 0);
;         asm volatile("s_waitcnt vmcnt(0)" ::: "memory");
;         __syncthreads();
;       }
;       for (int kt = 0; kt < nk; ++kt) {
;         const int buf = kt & 1;
;         if (kt + 1 < nk) issue(kt + 1, buf ^ 1);
;         else if (chain & 2) issue_at(nmt * 256, nnt * BN, 0, buf ^ 1);
;         compute2(buf);
;         asm volatile("s_waitcnt vmcnt(0)" ::: "memory");
;         __syncthreads();
;       }
.Lgemm_g1_1274:
	v_add_u32_e32 v233, s59, v199
	v_add_u32_e32 v230, v233, v175
	v_add_u32_e32 v234, v233, v174
	s_waitcnt lgkmcnt(3)
	v_mfma_f32_32x32x16_bf16 v[114:129], v[240:243], v[248:251], v[114:129]
	ds_read_b128 v[202:205], v230 offset:32768
	v_mfma_f32_32x32x16_bf16 v[98:113], v[244:247], v[248:251], v[98:113]
	ds_read_b128 v[206:209], v230 offset:36864
	s_waitcnt lgkmcnt(4)
	v_mfma_f32_32x32x16_bf16 v[82:97], v[240:243], v[214:217], v[82:97]
	ds_read_b128 v[210:213], v234
	v_mfma_f32_32x32x16_bf16 v[66:81], v[244:247], v[214:217], v[66:81]
	ds_read_b128 v[214:217], v234 offset:4096
	s_waitcnt lgkmcnt(5)
	v_mfma_f32_32x32x16_bf16 v[50:65], v[240:243], v[218:221], v[50:65]
	v_mfma_f32_32x32x16_bf16 v[34:49], v[244:247], v[218:221], v[34:49]
	ds_read_b128 v[218:221], v234 offset:8192
	s_waitcnt lgkmcnt(5)
	v_mfma_f32_32x32x16_bf16 v[18:33], v[240:243], v[222:225], v[18:33]
	v_mfma_f32_32x32x16_bf16 v[2:17], v[244:247], v[222:225], v[2:17]
	ds_read_b128 v[222:225], v234 offset:12288
	v_add_u32_e32 v233, s59, v176
	v_add_u32_e32 v230, v233, v175
	v_add_u32_e32 v234, v233, v174
	s_waitcnt lgkmcnt(3)
	v_mfma_f32_32x32x16_bf16 v[114:129], v[202:205], v[210:213], v[114:129]
	ds_read_b128 v[240:243], v230 offset:32768
	v_mfma_f32_32x32x16_bf16 v[98:113], v[206:209], v[210:213], v[98:113]
	ds_read_b128 v[244:247], v230 offset:36864
	s_waitcnt lgkmcnt(4)
	v_mfma_f32_32x32x16_bf16 v[82:97], v[202:205], v[214:217], v[82:97]
	ds_read_b128 v[248:251], v234
	v_mfma_f32_32x32x16_bf16 v[66:81], v[206:209], v[214:217], v[66:81]
	ds_read_b128 v[214:217], v234 offset:4096
	s_waitcnt lgkmcnt(5)
	v_mfma_f32_32x32x16_bf16 v[50:65], v[202:205], v[218:221], v[50:65]
	v_mfma_f32_32x32x16_bf16 v[34:49], v[206:209], v[218:221], v[34:49]
	ds_read_b128 v[218:221], v234 offset:8192
	s_waitcnt lgkmcnt(5)
	v_mfma_f32_32x32x16_bf16 v[18:33], v[202:205], v[222:225], v[18:33]
	v_mfma_f32_32x32x16_bf16 v[2:17], v[206:209], v[222:225], v[2:17]
	ds_read_b128 v[222:225], v234 offset:12288
	s_waitcnt vmcnt(0)
	s_waitcnt vmcnt(0) lgkmcnt(0)
	s_barrier
	s_cbranch_scc1 .Lgemm_exit_1274
	s_and_b32 s59, s56, 0x10000
	s_xor_b32 s60, s59, 0x10000
	s_add_i32 s57, s58, 1
	s_add_i32 s60, s60, 0
	s_cmp_lt_u32 s58, 21
	s_cselect_b64 vcc, -1, 0
	v_add_u32_e32 v233, s59, v201
	v_add_u32_e32 v230, v233, v175
	v_add_u32_e32 v234, v233, v174
	ds_read_b128 v[202:205], v230 offset:32768
	ds_read_b128 v[206:209], v230 offset:36864
	ds_read_b128 v[210:213], v234
	v_mfma_f32_32x32x16_bf16 v[114:129], v[240:243], v[248:251], v[114:129]
	s_add_i32 s66, s60, 0x8000
	v_lshl_add_u64 v[226:227], v[160:161], 0, s[2:3]
	v_lshl_add_u64 v[228:229], v[144:145], 0, s[2:3]
	v_cndmask_b32_e32 v227, v229, v227, vcc
	v_cndmask_b32_e32 v226, v228, v226, vcc
	v_lshl_add_u64 v[226:227], v[0:1], 1, v[226:227]
	s_add_i32 m0, s60, s62
	v_mfma_f32_32x32x16_bf16 v[98:113], v[244:247], v[248:251], v[98:113]
	v_lshl_add_u64 v[228:229], v[142:143], 0, s[2:3]
	global_load_lds_dwordx4 v[226:227], off
	v_lshl_add_u64 v[226:227], v[158:159], 0, s[2:3]
	v_cndmask_b32_e32 v227, v229, v227, vcc
	v_cndmask_b32_e32 v226, v228, v226, vcc
	v_lshl_add_u64 v[226:227], v[130:131], 1, v[226:227]
	s_add_i32 m0, s60, s63
	v_mfma_f32_32x32x16_bf16 v[82:97], v[240:243], v[214:217], v[82:97]
	v_lshl_add_u64 v[228:229], v[140:141], 0, s[2:3]
	global_load_lds_dwordx4 v[226:227], off
	v_lshl_add_u64 v[226:227], v[156:157], 0, s[2:3]
	v_cndmask_b32_e32 v227, v229, v227, vcc
	v_cndmask_b32_e32 v226, v228, v226, vcc
	v_lshl_add_u64 v[226:227], v[132:133], 1, v[226:227]
	s_add_i32 m0, s60, s64
	v_mfma_f32_32x32x16_bf16 v[66:81], v[244:247], v[214:217], v[66:81]
	ds_read_b128 v[214:217], v234 offset:4096
	v_lshl_add_u64 v[228:229], v[138:139], 0, s[2:3]
	global_load_lds_dwordx4 v[226:227], off
	v_lshl_add_u64 v[226:227], v[154:155], 0, s[2:3]
	v_cndmask_b32_e32 v226, v228, v226, vcc
	v_cndmask_b32_e32 v227, v229, v227, vcc
	s_add_i32 m0, s60, s65
	v_lshl_add_u64 v[226:227], v[134:135], 1, v[226:227]
	v_mfma_f32_32x32x16_bf16 v[50:65], v[240:243], v[218:221], v[50:65]
	global_load_lds_dwordx4 v[226:227], off
	s_add_i32 m0, s66, s62
	v_lshl_add_u64 v[226:227], v[146:147], 0, s[2:3]
	global_load_lds_dwordx4 v[226:227], off
	s_add_i32 m0, s66, s63
	v_lshl_add_u64 v[226:227], v[148:149], 0, s[2:3]
	global_load_lds_dwordx4 v[226:227], off
	v_mfma_f32_32x32x16_bf16 v[34:49], v[244:247], v[218:221], v[34:49]
	ds_read_b128 v[218:221], v234 offset:8192
	s_add_i32 m0, s66, s64
	v_lshl_add_u64 v[226:227], v[150:151], 0, s[2:3]
	global_load_lds_dwordx4 v[226:227], off
	v_lshl_add_u64 v[226:227], v[152:153], 0, s[2:3]
	s_add_i32 m0, s66, s65
	s_add_i32 s58, s59, 0
	global_load_lds_dwordx4 v[226:227], off
	v_mfma_f32_32x32x16_bf16 v[18:33], v[240:243], v[222:225], v[18:33]
	v_mfma_f32_32x32x16_bf16 v[2:17], v[244:247], v[222:225], v[2:17]
	ds_read_b128 v[222:225], v234 offset:12288
	s_branch .Lgemm_rot_1274

; #define MFMA(a, b, c) __builtin_amdgcn_mfma_f32_32x32x16_bf16((a), (b), (c), 0, 0, 0)
;     ...
;     auto compute2 = [&](int buf) {
;       const char* lb = L0 + buf * BUFB;
; #pragma unroll
;       for (int ks = 0; ks < 4; ++ks) {
;         const int c = ks * 2 + hh;
;         bf16x8 wf[2], xf[MI];
; #pragma unroll
;         for (int j = 0; j < 2; ++j) { const int r = wn * 64 + j * 32 + l32; wf[j] = *(const bf16x8*)(lb + 256 * 128 + r * 128 + ((c ^ ((r >> 1) & 7)) << 4)); }
; #pragma unroll
;         for (int i = 0; i < MI; ++i) { const int r = wm * (MI * 32) + i * 32 + l32; xf[i] = *(const bf16x8*)(lb + r * 128 + ((c ^ ((r >> 1) & 7)) << 4)); }
; #pragma unroll
;         for (int i = 0; i < MI; ++i) {
;           acc[i][0] = MFMA(wf[0], xf[i], acc[i][0]);
;           acc[i][1] = MFMA(wf[1], xf[i], acc[i][1]);
;         }
;       }
;     };
;     if (NBUF == 3) {
;       issue(0, 0);
;       if (nk > 1) { issue(1, 1); if (BN == 128) asm volatile("s_waitcnt vmcnt(6)" ::: "memory"); else asm volatile("s_waitcnt vmcnt(5)" ::: "memory"); }
;       else asm volatile("s_waitcnt vmcnt(0)" ::: "memory");
;       asm volatile("s_waitcnt lgkmcnt(0)" ::: "memory");
;       __builtin_amdgcn_s_barrier();
;       int buf = 0;
;       for (int kt = 0; kt < nk; ++kt) {
;         const int b2 = buf == 0 ? 2 : buf - 1;
;         if (kt + 2 < nk) issue(kt + 2, b2);
;         compute2(buf);
;         if (kt + 2 < nk) { if (BN == 128) asm volatile("s_waitcnt vmcnt(6)" ::: "memory"); else asm volatile("s_waitcnt vmcnt(5)" ::: "memory"); }
;         else asm volatile("s_waitcnt vmcnt(0)" ::: "memory");
;         asm volatile("s_waitcnt lgkmcnt(0)" ::: "memory");
;         __builtin_amdgcn_s_barrier();
;         buf = buf == 2 ? 0 : buf + 1;
;       }
;     } else {
;       if (!(chain & 1)) {
;         issue(0, 0);
;         asm volatile("s_waitcnt vmcnt(0)" ::: "memory");
;         __syncthreads();
;       }
;       for (int kt = 0; kt < nk; ++kt) {
;         const int buf = kt & 1;
;         if (kt + 1 < nk) issue(kt + 1, buf ^ 1);
;         else if (chain & 2) issue_at(nmt * 256, nnt * BN, 0, buf ^ 1);
;         compute2(buf);
;         asm volatile("s_waitcnt vmcnt(0)" ::: "memory");
;         __syncthreads();
;       }
.Lgemm_g1_1371:
	v_add_u32_e32 v0, s17, v172
	v_add_u32_e32 v175, v0, v170
	v_add_u32_e32 v0, v0, v169
	s_waitcnt lgkmcnt(3)
	v_mfma_f32_32x32x16_bf16 v[114:129], v[224:227], v[232:235], v[114:129]
	ds_read_b128 v[200:203], v175 offset:32768
	v_mfma_f32_32x32x16_bf16 v[98:113], v[228:231], v[232:235], v[98:113]
	ds_read_b128 v[204:207], v175 offset:36864
	s_waitcnt lgkmcnt(4)
	v_mfma_f32_32x32x16_bf16 v[82:97], v[224:227], v[240:243], v[82:97]
	ds_read_b128 v[208:211], v0
	v_mfma_f32_32x32x16_bf16 v[66:81], v[228:231], v[240:243], v[66:81]
	ds_read_b128 v[212:215], v0 offset:4096
	s_waitcnt lgkmcnt(5)
	v_mfma_f32_32x32x16_bf16 v[50:65], v[224:227], v[244:247], v[50:65]
	ds_read_b128 v[216:219], v0 offset:8192
	v_mfma_f32_32x32x16_bf16 v[34:49], v[228:231], v[244:247], v[34:49]
	ds_read_b128 v[220:223], v0 offset:12288
	s_waitcnt lgkmcnt(6)
	v_mfma_f32_32x32x16_bf16 v[18:33], v[224:227], v[248:251], v[18:33]
	v_mfma_f32_32x32x16_bf16 v[2:17], v[228:231], v[248:251], v[2:17]
	v_add_u32_e32 v0, s17, v171
	v_add_u32_e32 v175, v0, v170
	v_add_u32_e32 v0, v0, v169
	s_waitcnt lgkmcnt(3)
	v_mfma_f32_32x32x16_bf16 v[114:129], v[200:203], v[208:211], v[114:129]
	ds_read_b128 v[224:227], v175 offset:32768
	v_mfma_f32_32x32x16_bf16 v[98:113], v[204:207], v[208:211], v[98:113]
	ds_read_b128 v[228:231], v175 offset:36864
	s_waitcnt lgkmcnt(4)
	v_mfma_f32_32x32x16_bf16 v[82:97], v[200:203], v[212:215], v[82:97]
	ds_read_b128 v[232:235], v0
	v_mfma_f32_32x32x16_bf16 v[66:81], v[204:207], v[212:215], v[66:81]
	ds_read_b128 v[240:243], v0 offset:4096
	s_waitcnt lgkmcnt(5)
	v_mfma_f32_32x32x16_bf16 v[50:65], v[200:203], v[216:219], v[50:65]
	ds_read_b128 v[244:247], v0 offset:8192
	v_mfma_f32_32x32x16_bf16 v[34:49], v[204:207], v[216:219], v[34:49]
	ds_read_b128 v[248:251], v0 offset:12288
	s_waitcnt lgkmcnt(6)
	v_mfma_f32_32x32x16_bf16 v[18:33], v[200:203], v[220:223], v[18:33]
	v_mfma_f32_32x32x16_bf16 v[2:17], v[204:207], v[220:223], v[2:17]
	s_waitcnt vmcnt(0)
	s_waitcnt vmcnt(0) lgkmcnt(0)
	s_barrier
	s_cbranch_scc1 .Lgemm_exit_1371
	s_and_b32 s17, s16, 0x10000
	s_xor_b32 s43, s17, 0x10000
	s_add_i32 s43, s43, 0
	s_add_i32 s17, s17, 0
	v_add_u32_e32 v0, s17, v174
	v_add_u32_e32 v175, v0, v170
	v_add_u32_e32 v0, v0, v169
	ds_read_b128 v[200:203], v175 offset:32768
	ds_read_b128 v[204:207], v175 offset:36864
	ds_read_b128 v[208:211], v0
	ds_read_b128 v[212:215], v0 offset:4096
	ds_read_b128 v[216:219], v0 offset:8192
	ds_read_b128 v[220:223], v0 offset:12288
	v_mfma_f32_32x32x16_bf16 v[114:129], v[224:227], v[232:235], v[114:129]
	s_add_i32 s64, s43, 0x8000
	s_add_i32 m0, s43, s60
	v_lshl_add_u64 v[176:177], v[152:153], 0, s[10:11]
	global_load_lds_dwordx4 v[176:177], off
	s_add_i32 m0, s43, s61
	v_mfma_f32_32x32x16_bf16 v[98:113], v[228:231], v[232:235], v[98:113]
	v_lshl_add_u64 v[176:177], v[150:151], 0, s[10:11]
	global_load_lds_dwordx4 v[176:177], off
	s_add_i32 m0, s43, s62
	v_lshl_add_u64 v[176:177], v[148:149], 0, s[10:11]
	global_load_lds_dwordx4 v[176:177], off
	v_mfma_f32_32x32x16_bf16 v[82:97], v[224:227], v[240:243], v[82:97]
	s_add_i32 m0, s43, s63
	v_lshl_add_u64 v[176:177], v[146:147], 0, s[10:11]
	global_load_lds_dwordx4 v[176:177], off
	s_add_i32 m0, s64, s60
	v_lshl_add_u64 v[176:177], v[144:145], 0, s[10:11]
	v_mfma_f32_32x32x16_bf16 v[66:81], v[228:231], v[240:243], v[66:81]
	global_load_lds_dwordx4 v[176:177], off
	s_add_i32 m0, s64, s61
	v_lshl_add_u64 v[176:177], v[142:143], 0, s[10:11]
	global_load_lds_dwordx4 v[176:177], off
	s_add_i32 m0, s64, s62
	v_mfma_f32_32x32x16_bf16 v[50:65], v[224:227], v[244:247], v[50:65]
	v_lshl_add_u64 v[176:177], v[140:141], 0, s[10:11]
	global_load_lds_dwordx4 v[176:177], off
	s_add_i32 m0, s64, s63
	v_lshl_add_u64 v[176:177], v[138:139], 0, s[10:11]
	global_load_lds_dwordx4 v[176:177], off
	v_mfma_f32_32x32x16_bf16 v[34:49], v[228:231], v[244:247], v[34:49]
	v_mfma_f32_32x32x16_bf16 v[18:33], v[224:227], v[248:251], v[18:33]
	v_mfma_f32_32x32x16_bf16 v[2:17], v[228:231], v[248:251], v[2:17]
	s_branch .Lgemm_rot_1371
